# combined: v13 + mixer single-wait/vmcnt(8) tweaks + progressive EpiResid waits + P7 conv taps staged in LDS (no vmcnt waits in epilogue) with early rstd scaling + static priority for waves 0-3 (per-se
# speedup vs baseline: 1.0329x; 1.0223x over previous
; #define PG8_STAGE(bufoff, gbase, voff) do { _Pragma("unroll") for (int _i = 0; _i < 2; ++_i) \
;         __builtin_amdgcn_global_load_lds((const unsigned*)((const char*)(gbase) + (voff)[_i]), (PG8_LAS unsigned*)(lds + (bufoff) + ldsw + _i * 8192), 16, 0, 0); } while (0)
; #define PG8_LDA(dst, b, h) do { _Pragma("unroll") for (int m = 0; m < 4; ++m) _Pragma("unroll") for (int k = 0; k < 2; ++k) dst[m][k] = *(const PG8_LAS bf16x8*)(lds + PG8_SA(b, h) + aoff + m * 2048 + k * 1024); } while (0)
; #define PG8_LDB(dst, b, h) do { _Pragma("unroll") for (int n = 0; n < 2; ++n) _Pragma("unroll") for (int k = 0; k < 2; ++k) dst[n][k] = *(const PG8_LAS bf16x8*)(lds + PG8_SB(b, h) + boff + n * 2048 + k * 1024); } while (0)
; #define PG8_MMA(ai, bj, At, Bt) do { __builtin_amdgcn_s_setprio(1); _Pragma("unroll") for (int m = 0; m < 4; ++m) _Pragma("unroll") for (int n = 0; n < 2; ++n) _Pragma("unroll") for (int k = 0; k < 2; ++k) \
;         acc[ai][bj][m][n] = __builtin_amdgcn_mfma_f32_16x16x32_bf16(Bt[n][k], At[m][k], acc[ai][bj][m][n], 0, 0, 0); __builtin_amdgcn_s_setprio(0); } while (0)
; #define PG8_WAIT_V(n) asm volatile("s_waitcnt vmcnt(" #n ")" ::: "memory")
; #define PG8_WAIT_L(n) asm volatile("s_waitcnt lgkmcnt(" #n ")" ::: "memory")
; #define PG8_BAR __builtin_amdgcn_s_barrier()
; #define PG8_SCHED __builtin_amdgcn_sched_barrier(0)
;     __device__ __forceinline__ void operator()(const f32x4 (&acc)[2][2][4][2], const Unit& u, int wr, int wc, int fr, int fq) const {
;     ...
;         for (int bj = 0; bj < 2; ++bj) { const int col = bj * FF + gcol;
;             w0[bj] = *(const f32x4*)(cw + col); w1[bj] = *(const f32x4*)(cw + FF2 + col); w2[bj] = *(const f32x4*)(cw + 2 * FF2 + col); bb[bj] = *(const f32x4*)(cb + col); }
; template <class Epi, class Sched, bool ALIGN_EPI = false, bool SP2 = false>
; __device__ __forceinline__ void gemm_phase(PG8_LAS unsigned char* lds, const Gemm g, const Sched& S, const Epi& E, int wave_in) {
;     ...
;             PG8_LDB(B0, 0, 0); PG8_LDB(B1, 0, 1); PG8_SCHED; PG8_LDA(At, 0, 0); PG8_STAGE(PG8_SA(1, 1), a1 + hstep, voffA);
;             PG8_WAIT_V(8); PG8_WAIT_L(0); PG8_BAR; PG8_MMA(0, 0, At, B0); PG8_MMA(0, 1, At, B1); PG8_BAR; PG8_SCHED;
;             PG8_LDA(At, 0, 1); PG8_STAGE(PG8_SB(0, 0), b2, voffB); PG8_STAGE(PG8_SB(0, 1), b2 + hstep, voffB); PG8_STAGE(PG8_SA(0, 0), a2, voffA);
.LBB0_896:
	s_ashr_i32 s11, s10, 31
	s_lshl_b64 s[18:19], s[10:11], 19
	s_add_u32 s66, s6, s18
	s_addc_u32 s67, s72, s19
	s_and_b64 s[18:19], s[46:47], exec
	s_cselect_b32 s11, s67, s1
	s_cselect_b32 s34, s66, s0
	s_ashr_i32 s5, s4, 31
	s_lshl_b64 s[18:19], s[4:5], 19
	s_add_u32 s38, s73, s18
	s_addc_u32 s39, s74, s19
	s_and_b64 s[18:19], s[46:47], exec
	s_cselect_b32 s5, s39, s79
	s_cselect_b32 s53, s38, s78
	s_add_u32 s81, s78, 0x100
	s_addc_u32 s18, s79, 0
	s_add_u32 vcc_lo, s0, 0x40080
	s_addc_u32 vcc_hi, s1, 0
	s_mov_b32 s19, -2
	s_add_u32 s0, vcc_lo, 0xfffc0080
	s_addc_u32 s1, vcc_hi, -1
	s_add_i32 s76, s35, 0x100
	s_cmp_eq_u32 s19, 12
	s_cselect_b32 s79, s11, s1
	s_cselect_b32 s78, s34, s0
	s_cselect_b32 s1, s5, s18
	s_cselect_b32 s0, s53, s81
	s_add_i32 s29, s90, 0x100
	v_add_u32_e32 v140, s76, v207
	v_add_u32_e32 v156, s29, v207
	ds_read_b128 v[128:131], v140
	ds_read_b128 v[132:135], v140 offset:1024
	ds_read_b128 v[136:139], v140 offset:2048
	ds_read_b128 v[140:143], v140 offset:3072
	ds_read_b128 v[144:147], v156
	ds_read_b128 v[148:151], v156 offset:1024
	ds_read_b128 v[152:155], v156 offset:2048
	ds_read_b128 v[156:159], v156 offset:3072
	v_lshl_add_u64 v[190:191], vcc, 0, v[176:177]
	s_add_i32 m0, s33, 0xc000
	ds_read_b128 v[160:163], v219
	ds_read_b128 v[164:167], v219 offset:1024
	ds_read_b128 v[178:181], v219 offset:2048
	ds_read_b128 v[182:185], v219 offset:3072
	ds_read_b128 v[186:189], v219 offset:4096
	ds_read_b128 v[198:201], v219 offset:5120
	ds_read_b128 v[202:205], v219 offset:6144
	ds_read_b128 v[220:223], v219 offset:7168
	global_load_lds_dwordx4 v[190:191], off
	v_lshl_add_u64 v[190:191], vcc, 0, v[174:175]
	s_add_i32 m0, s33, 0xe000
	s_nop 0
	global_load_lds_dwordx4 v[190:191], off
	s_waitcnt vmcnt(8)
	s_waitcnt lgkmcnt(0)
	s_barrier
	s_waitcnt lgkmcnt(0)
	v_mfma_f32_16x16x32_bf16 v[124:127], v[128:131], v[160:163], 0
	v_mfma_f32_16x16x32_bf16 v[60:63], v[136:139], v[160:163], 0
	v_mfma_f32_16x16x32_bf16 v[116:119], v[128:131], v[178:181], 0
	v_mfma_f32_16x16x32_bf16 v[52:55], v[136:139], v[178:181], 0
	v_mfma_f32_16x16x32_bf16 v[108:111], v[128:131], v[186:189], 0
	v_mfma_f32_16x16x32_bf16 v[44:47], v[136:139], v[186:189], 0
	v_mfma_f32_16x16x32_bf16 v[100:103], v[128:131], v[202:205], 0
	v_mfma_f32_16x16x32_bf16 v[36:39], v[136:139], v[202:205], 0
	v_mfma_f32_16x16x32_bf16 v[124:127], v[132:135], v[164:167], v[124:127]
	v_mfma_f32_16x16x32_bf16 v[60:63], v[140:143], v[164:167], v[60:63]
	v_mfma_f32_16x16x32_bf16 v[116:119], v[132:135], v[182:185], v[116:119]
	v_mfma_f32_16x16x32_bf16 v[52:55], v[140:143], v[182:185], v[52:55]
	v_mfma_f32_16x16x32_bf16 v[108:111], v[132:135], v[198:201], v[108:111]
	v_mfma_f32_16x16x32_bf16 v[44:47], v[140:143], v[198:201], v[44:47]
	v_mfma_f32_16x16x32_bf16 v[100:103], v[132:135], v[220:223], v[100:103]
	v_mfma_f32_16x16x32_bf16 v[36:39], v[140:143], v[220:223], v[36:39]
	v_mfma_f32_16x16x32_bf16 v[120:123], v[144:147], v[160:163], 0
	v_mfma_f32_16x16x32_bf16 v[56:59], v[152:155], v[160:163], 0
	v_mfma_f32_16x16x32_bf16 v[112:115], v[144:147], v[178:181], 0
	v_mfma_f32_16x16x32_bf16 v[48:51], v[152:155], v[178:181], 0
	v_mfma_f32_16x16x32_bf16 v[104:107], v[144:147], v[186:189], 0
	v_mfma_f32_16x16x32_bf16 v[40:43], v[152:155], v[186:189], 0
	v_mfma_f32_16x16x32_bf16 v[96:99], v[144:147], v[202:205], 0
	v_mfma_f32_16x16x32_bf16 v[32:35], v[152:155], v[202:205], 0
	v_mfma_f32_16x16x32_bf16 v[120:123], v[148:151], v[164:167], v[120:123]
	v_mfma_f32_16x16x32_bf16 v[56:59], v[156:159], v[164:167], v[56:59]
	v_mfma_f32_16x16x32_bf16 v[112:115], v[148:151], v[182:185], v[112:115]
	v_mfma_f32_16x16x32_bf16 v[48:51], v[156:159], v[182:185], v[48:51]
	v_mfma_f32_16x16x32_bf16 v[104:107], v[148:151], v[198:201], v[104:107]
	v_mfma_f32_16x16x32_bf16 v[40:43], v[156:159], v[198:201], v[40:43]
	v_mfma_f32_16x16x32_bf16 v[96:99], v[148:151], v[220:223], v[96:99]
	v_mfma_f32_16x16x32_bf16 v[32:35], v[156:159], v[220:223], v[32:35]
	s_barrier
	v_readfirstlane_b32 s83, v208
	s_lshl_b32 s82, s69, 9
	v_and_b32_e32 v212, 31, v252
	v_and_b32_e32 v249, 32, v252
	v_lshlrev_b32_e32 v212, 4, v212
	v_mul_u32_u24_e32 v249, 0x160, v249
	s_cmp_eq_u32 s83, 32
	s_cselect_b32 s42, s16, s14
	s_cselect_b32 s43, s17, s15
	s_cmp_eq_u32 s83, 64
	s_cselect_b32 s42, s92, s42
	s_cselect_b32 s43, s93, s43
	s_cmp_eq_u32 s83, 0x60
	s_cselect_b32 s42, s60, s42
	s_cselect_b32 s43, s61, s43
	s_add_u32 s42, s42, s82
	s_addc_u32 s43, s43, 0
	v_add_u32_e32 v212, v212, v249
	s_lshl_b32 s83, s83, 5
	s_add_i32 m0, s83, 0x20100
	s_nop 0
	global_load_lds_dwordx4 v212, s[42:43]
	s_add_i32 s76, s76, s75
	v_lshl_add_u64 v[190:191], s[0:1], 0, v[192:193]
	s_mov_b32 m0, s76
	ds_read_b128 v[160:163], v219 offset:16384
	ds_read_b128 v[164:167], v219 offset:17408
	ds_read_b128 v[178:181], v219 offset:18432
	ds_read_b128 v[182:185], v219 offset:19456
	ds_read_b128 v[186:189], v219 offset:20480
	ds_read_b128 v[198:201], v219 offset:21504
	ds_read_b128 v[202:205], v219 offset:22528
	ds_read_b128 v[220:223], v219 offset:23552
	global_load_lds_dwordx4 v[190:191], off
	s_add_i32 m0, s76, 0x2000
	s_add_u32 s76, s0, 0x40000
	v_lshl_add_u64 v[194:195], s[0:1], 0, v[168:169]
	s_addc_u32 s77, s1, 0
	s_add_i32 s29, s29, s75
	global_load_lds_dwordx4 v[194:195], off
	v_lshl_add_u64 v[196:197], s[76:77], 0, v[192:193]
	s_mov_b32 m0, s29
	v_lshl_add_u64 v[224:225], s[78:79], 0, v[170:171]
	global_load_lds_dwordx4 v[196:197], off
	v_lshl_add_u64 v[196:197], s[76:77], 0, v[168:169]
	s_add_i32 m0, s29, 0x2000
	s_nop 0
	global_load_lds_dwordx4 v[196:197], off
	v_lshl_add_u64 v[196:197], s[78:79], 0, v[172:173]
	s_mov_b32 m0, s33
	s_nop 0
	global_load_lds_dwordx4 v[196:197], off
	s_mov_b32 m0, s62
	s_nop 0
	global_load_lds_dwordx4 v[224:225], off
	s_waitcnt vmcnt(8)
	s_waitcnt lgkmcnt(0)
	s_barrier
; #define PG8_STAGE(bufoff, gbase, voff) do { _Pragma("unroll") for (int _i = 0; _i < 2; ++_i) \
;         __builtin_amdgcn_global_load_lds((const unsigned*)((const char*)(gbase) + (voff)[_i]), (PG8_LAS unsigned*)(lds + (bufoff) + ldsw + _i * 8192), 16, 0, 0); } while (0)
; #define PG8_LDA(dst, b, h) do { _Pragma("unroll") for (int m = 0; m < 4; ++m) _Pragma("unroll") for (int k = 0; k < 2; ++k) dst[m][k] = *(const PG8_LAS bf16x8*)(lds + PG8_SA(b, h) + aoff + m * 2048 + k * 1024); } while (0)
; #define PG8_LDB(dst, b, h) do { _Pragma("unroll") for (int n = 0; n < 2; ++n) _Pragma("unroll") for (int k = 0; k < 2; ++k) dst[n][k] = *(const PG8_LAS bf16x8*)(lds + PG8_SB(b, h) + boff + n * 2048 + k * 1024); } while (0)
; #define PG8_MMA(ai, bj, At, Bt) do { __builtin_amdgcn_s_setprio(1); _Pragma("unroll") for (int m = 0; m < 4; ++m) _Pragma("unroll") for (int n = 0; n < 2; ++n) _Pragma("unroll") for (int k = 0; k < 2; ++k) \
;         acc[ai][bj][m][n] = __builtin_amdgcn_mfma_f32_16x16x32_bf16(Bt[n][k], At[m][k], acc[ai][bj][m][n], 0, 0, 0); __builtin_amdgcn_s_setprio(0); } while (0)
; #define PG8_WAIT_V(n) asm volatile("s_waitcnt vmcnt(" #n ")" ::: "memory")
; #define PG8_WAIT_L(n) asm volatile("s_waitcnt lgkmcnt(" #n ")" ::: "memory")
; #define PG8_BAR __builtin_amdgcn_s_barrier()
; #define PG8_SCHED __builtin_amdgcn_sched_barrier(0)
; template <class Epi, class Sched, bool ALIGN_EPI = false, bool SP2 = false>
; __device__ __forceinline__ void gemm_phase(PG8_LAS unsigned char* lds, const Gemm g, const Sched& S, const Epi& E, int wave_in) {
;     ...
;             PG8_WAIT_V(8); PG8_WAIT_L(0); PG8_BAR; PG8_MMA(1, 0, At, B0); PG8_MMA(1, 1, At, B1); PG8_BAR; PG8_SCHED;
;             PG8_LDB(B0, 1, 0); PG8_LDB(B1, 1, 1); PG8_SCHED; PG8_LDA(At, 1, 0); PG8_STAGE(PG8_SA(0, 1), a2 + hstep, voffA);
;             PG8_WAIT_V(8); PG8_WAIT_L(0); PG8_BAR; PG8_MMA(0, 0, At, B0); PG8_MMA(0, 1, At, B1); PG8_BAR; PG8_SCHED;
	s_waitcnt lgkmcnt(0)
	v_mfma_f32_16x16x32_bf16 v[92:95], v[128:131], v[160:163], 0
	v_mfma_f32_16x16x32_bf16 v[28:31], v[136:139], v[160:163], 0
	v_mfma_f32_16x16x32_bf16 v[84:87], v[128:131], v[178:181], 0
	v_mfma_f32_16x16x32_bf16 v[20:23], v[136:139], v[178:181], 0
	v_mfma_f32_16x16x32_bf16 v[76:79], v[128:131], v[186:189], 0
	v_mfma_f32_16x16x32_bf16 v[12:15], v[136:139], v[186:189], 0
	v_mfma_f32_16x16x32_bf16 v[68:71], v[128:131], v[202:205], 0
	v_mfma_f32_16x16x32_bf16 v[4:7], v[136:139], v[202:205], 0
	v_mfma_f32_16x16x32_bf16 v[92:95], v[132:135], v[164:167], v[92:95]
	v_mfma_f32_16x16x32_bf16 v[28:31], v[140:143], v[164:167], v[28:31]
	v_mfma_f32_16x16x32_bf16 v[84:87], v[132:135], v[182:185], v[84:87]
	v_mfma_f32_16x16x32_bf16 v[20:23], v[140:143], v[182:185], v[20:23]
	v_mfma_f32_16x16x32_bf16 v[76:79], v[132:135], v[198:201], v[76:79]
	v_mfma_f32_16x16x32_bf16 v[12:15], v[140:143], v[198:201], v[12:15]
	v_mfma_f32_16x16x32_bf16 v[68:71], v[132:135], v[220:223], v[68:71]
	v_mfma_f32_16x16x32_bf16 v[4:7], v[140:143], v[220:223], v[4:7]
	v_mfma_f32_16x16x32_bf16 v[88:91], v[144:147], v[160:163], 0
	v_mfma_f32_16x16x32_bf16 v[24:27], v[152:155], v[160:163], 0
	v_mfma_f32_16x16x32_bf16 v[80:83], v[144:147], v[178:181], 0
	v_mfma_f32_16x16x32_bf16 v[16:19], v[152:155], v[178:181], 0
	v_mfma_f32_16x16x32_bf16 v[72:75], v[144:147], v[186:189], 0
	v_mfma_f32_16x16x32_bf16 v[8:11], v[152:155], v[186:189], 0
	v_mfma_f32_16x16x32_bf16 v[64:67], v[144:147], v[202:205], 0
	v_mfma_f32_16x16x32_bf16 v[0:3], v[152:155], v[202:205], 0
	v_mfma_f32_16x16x32_bf16 v[88:91], v[148:151], v[164:167], v[88:91]
	v_mfma_f32_16x16x32_bf16 v[24:27], v[156:159], v[164:167], v[24:27]
	v_mfma_f32_16x16x32_bf16 v[80:83], v[148:151], v[182:185], v[80:83]
	v_mfma_f32_16x16x32_bf16 v[16:19], v[156:159], v[182:185], v[16:19]
	v_mfma_f32_16x16x32_bf16 v[72:75], v[148:151], v[198:201], v[72:75]
	v_mfma_f32_16x16x32_bf16 v[8:11], v[156:159], v[198:201], v[8:11]
	v_mfma_f32_16x16x32_bf16 v[64:67], v[148:151], v[220:223], v[64:67]
	v_mfma_f32_16x16x32_bf16 v[0:3], v[156:159], v[220:223], v[0:3]
	s_barrier
	s_add_i32 s29, s65, 0x100
	s_add_i32 s2, s52, 0x100
	v_add_u32_e32 v140, s29, v207
	v_add_u32_e32 v156, s2, v207
	ds_read_b128 v[128:131], v140
	ds_read_b128 v[132:135], v140 offset:1024
	ds_read_b128 v[136:139], v140 offset:2048
	ds_read_b128 v[140:143], v140 offset:3072
	ds_read_b128 v[144:147], v156
	ds_read_b128 v[148:151], v156 offset:1024
	ds_read_b128 v[152:155], v156 offset:2048
	ds_read_b128 v[156:159], v156 offset:3072
	s_add_u32 s76, s78, 0x40000
	s_addc_u32 s77, s79, 0
	s_mov_b32 m0, s63
	v_lshl_add_u64 v[226:227], s[76:77], 0, v[172:173]
	ds_read_b128 v[160:163], v219 offset:32768
	ds_read_b128 v[164:167], v219 offset:33792
	ds_read_b128 v[178:181], v219 offset:34816
	ds_read_b128 v[182:185], v219 offset:35840
	ds_read_b128 v[186:189], v219 offset:36864
	ds_read_b128 v[198:201], v219 offset:37888
	ds_read_b128 v[202:205], v219 offset:38912
	ds_read_b128 v[220:223], v219 offset:39936
	global_load_lds_dwordx4 v[226:227], off
	v_lshl_add_u64 v[226:227], s[76:77], 0, v[170:171]
	s_mov_b32 m0, s31
	s_nop 0
	global_load_lds_dwordx4 v[226:227], off
	s_waitcnt vmcnt(8)
	s_waitcnt lgkmcnt(0)
	s_barrier
	s_waitcnt lgkmcnt(0)
	v_mfma_f32_16x16x32_bf16 v[124:127], v[128:131], v[160:163], v[124:127]
	v_mfma_f32_16x16x32_bf16 v[60:63], v[136:139], v[160:163], v[60:63]
	v_mfma_f32_16x16x32_bf16 v[116:119], v[128:131], v[178:181], v[116:119]
	v_mfma_f32_16x16x32_bf16 v[52:55], v[136:139], v[178:181], v[52:55]
	v_mfma_f32_16x16x32_bf16 v[108:111], v[128:131], v[186:189], v[108:111]
	v_mfma_f32_16x16x32_bf16 v[44:47], v[136:139], v[186:189], v[44:47]
	v_mfma_f32_16x16x32_bf16 v[100:103], v[128:131], v[202:205], v[100:103]
	v_mfma_f32_16x16x32_bf16 v[36:39], v[136:139], v[202:205], v[36:39]
	v_mfma_f32_16x16x32_bf16 v[124:127], v[132:135], v[164:167], v[124:127]
	v_mfma_f32_16x16x32_bf16 v[60:63], v[140:143], v[164:167], v[60:63]
	v_mfma_f32_16x16x32_bf16 v[116:119], v[132:135], v[182:185], v[116:119]
	v_mfma_f32_16x16x32_bf16 v[52:55], v[140:143], v[182:185], v[52:55]
	v_mfma_f32_16x16x32_bf16 v[108:111], v[132:135], v[198:201], v[108:111]
	v_mfma_f32_16x16x32_bf16 v[44:47], v[140:143], v[198:201], v[44:47]
	v_mfma_f32_16x16x32_bf16 v[100:103], v[132:135], v[220:223], v[100:103]
	v_mfma_f32_16x16x32_bf16 v[36:39], v[140:143], v[220:223], v[36:39]
	v_mfma_f32_16x16x32_bf16 v[120:123], v[144:147], v[160:163], v[120:123]
	v_mfma_f32_16x16x32_bf16 v[56:59], v[152:155], v[160:163], v[56:59]
	v_mfma_f32_16x16x32_bf16 v[112:115], v[144:147], v[178:181], v[112:115]
	v_mfma_f32_16x16x32_bf16 v[48:51], v[152:155], v[178:181], v[48:51]
	v_mfma_f32_16x16x32_bf16 v[104:107], v[144:147], v[186:189], v[104:107]
	v_mfma_f32_16x16x32_bf16 v[40:43], v[152:155], v[186:189], v[40:43]
	v_mfma_f32_16x16x32_bf16 v[96:99], v[144:147], v[202:205], v[96:99]
	v_mfma_f32_16x16x32_bf16 v[32:35], v[152:155], v[202:205], v[32:35]
	v_mfma_f32_16x16x32_bf16 v[120:123], v[148:151], v[164:167], v[120:123]
	v_mfma_f32_16x16x32_bf16 v[56:59], v[156:159], v[164:167], v[56:59]
	v_mfma_f32_16x16x32_bf16 v[112:115], v[148:151], v[182:185], v[112:115]
	v_mfma_f32_16x16x32_bf16 v[48:51], v[156:159], v[182:185], v[48:51]
	v_mfma_f32_16x16x32_bf16 v[104:107], v[148:151], v[198:201], v[104:107]
	v_mfma_f32_16x16x32_bf16 v[40:43], v[156:159], v[198:201], v[40:43]
	v_mfma_f32_16x16x32_bf16 v[96:99], v[148:151], v[220:223], v[96:99]
	v_mfma_f32_16x16x32_bf16 v[32:35], v[156:159], v[220:223], v[32:35]
	s_barrier
; #define PG8_STAGE(bufoff, gbase, voff) do { _Pragma("unroll") for (int _i = 0; _i < 2; ++_i) \
;         __builtin_amdgcn_global_load_lds((const unsigned*)((const char*)(gbase) + (voff)[_i]), (PG8_LAS unsigned*)(lds + (bufoff) + ldsw + _i * 8192), 16, 0, 0); } while (0)
; #define PG8_LDA(dst, b, h) do { _Pragma("unroll") for (int m = 0; m < 4; ++m) _Pragma("unroll") for (int k = 0; k < 2; ++k) dst[m][k] = *(const PG8_LAS bf16x8*)(lds + PG8_SA(b, h) + aoff + m * 2048 + k * 1024); } while (0)
; #define PG8_MMA(ai, bj, At, Bt) do { __builtin_amdgcn_s_setprio(1); _Pragma("unroll") for (int m = 0; m < 4; ++m) _Pragma("unroll") for (int n = 0; n < 2; ++n) _Pragma("unroll") for (int k = 0; k < 2; ++k) \
;         acc[ai][bj][m][n] = __builtin_amdgcn_mfma_f32_16x16x32_bf16(Bt[n][k], At[m][k], acc[ai][bj][m][n], 0, 0, 0); __builtin_amdgcn_s_setprio(0); } while (0)
; #define PG8_WAIT_V(n) asm volatile("s_waitcnt vmcnt(" #n ")" ::: "memory")
; #define PG8_WAIT_L(n) asm volatile("s_waitcnt lgkmcnt(" #n ")" ::: "memory")
; #define PG8_BAR __builtin_amdgcn_s_barrier()
; #define PG8_SCHED __builtin_amdgcn_sched_barrier(0)
; template <class Epi, class Sched, bool ALIGN_EPI = false, bool SP2 = false>
; __device__ __forceinline__ void gemm_phase(PG8_LAS unsigned char* lds, const Gemm g, const Sched& S, const Epi& E, int wave_in) {
;     ...
;         for (int t = 0; t < nt; t += 2) {
;             const bool last = (t == nt - 2);
;     ...
;             PG8_LDA(At, 1, 1); PG8_STAGE(PG8_SB(1, 0), b3, voffB); PG8_STAGE(PG8_SB(1, 1), b3 + hstep, voffB); PG8_STAGE(PG8_SA(1, 0), a3, voffA);
;             PG8_WAIT_V(8); PG8_WAIT_L(0); PG8_BAR; PG8_MMA(1, 0, At, B0); PG8_MMA(1, 1, At, B1); PG8_BAR; PG8_SCHED;
	s_add_i32 s29, s29, s75
	v_lshl_add_u64 v[190:191], v[190:191], 0, s[88:89]
	s_mov_b32 m0, s29
	ds_read_b128 v[160:163], v219 offset:49152
	ds_read_b128 v[164:167], v219 offset:50176
	ds_read_b128 v[178:181], v219 offset:51200
	ds_read_b128 v[182:185], v219 offset:52224
	ds_read_b128 v[186:189], v219 offset:53248
	ds_read_b128 v[198:201], v219 offset:54272
	ds_read_b128 v[202:205], v219 offset:55296
	ds_read_b128 v[220:223], v219 offset:56320
	global_load_lds_dwordx4 v[190:191], off
	s_add_i32 m0, s29, 0x2000
	s_add_u32 s0, s0, 0x40080
	v_lshl_add_u64 v[190:191], v[194:195], 0, s[88:89]
	s_addc_u32 s1, s1, 0
	s_add_i32 s2, s2, s75
	global_load_lds_dwordx4 v[190:191], off
	v_lshl_add_u64 v[190:191], s[0:1], 0, v[192:193]
	s_mov_b32 m0, s2
	s_nop 0
	global_load_lds_dwordx4 v[190:191], off
	v_lshl_add_u64 v[190:191], s[0:1], 0, v[168:169]
	s_add_i32 m0, s2, 0x2000
	s_nop 0
	global_load_lds_dwordx4 v[190:191], off
	v_lshl_add_u64 v[190:191], v[196:197], 0, s[88:89]
	s_mov_b32 m0, s9
	s_nop 0
	global_load_lds_dwordx4 v[190:191], off
	v_lshl_add_u64 v[190:191], v[224:225], 0, s[88:89]
	s_mov_b32 m0, s96
	s_nop 0
	global_load_lds_dwordx4 v[190:191], off
	s_waitcnt vmcnt(8)
	s_waitcnt lgkmcnt(0)
	s_barrier
	s_waitcnt lgkmcnt(0)
	v_mfma_f32_16x16x32_bf16 v[92:95], v[128:131], v[160:163], v[92:95]
	v_mfma_f32_16x16x32_bf16 v[28:31], v[136:139], v[160:163], v[28:31]
	v_mfma_f32_16x16x32_bf16 v[84:87], v[128:131], v[178:181], v[84:87]
	v_mfma_f32_16x16x32_bf16 v[20:23], v[136:139], v[178:181], v[20:23]
	v_mfma_f32_16x16x32_bf16 v[76:79], v[128:131], v[186:189], v[76:79]
	v_mfma_f32_16x16x32_bf16 v[12:15], v[136:139], v[186:189], v[12:15]
	v_mfma_f32_16x16x32_bf16 v[68:71], v[128:131], v[202:205], v[68:71]
	v_mfma_f32_16x16x32_bf16 v[4:7], v[136:139], v[202:205], v[4:7]
	v_mfma_f32_16x16x32_bf16 v[92:95], v[132:135], v[164:167], v[92:95]
	v_mfma_f32_16x16x32_bf16 v[28:31], v[140:143], v[164:167], v[28:31]
	v_mfma_f32_16x16x32_bf16 v[84:87], v[132:135], v[182:185], v[84:87]
	v_mfma_f32_16x16x32_bf16 v[20:23], v[140:143], v[182:185], v[20:23]
	v_mfma_f32_16x16x32_bf16 v[76:79], v[132:135], v[198:201], v[76:79]
	v_mfma_f32_16x16x32_bf16 v[12:15], v[140:143], v[198:201], v[12:15]
	v_mfma_f32_16x16x32_bf16 v[68:71], v[132:135], v[220:223], v[68:71]
	v_mfma_f32_16x16x32_bf16 v[4:7], v[140:143], v[220:223], v[4:7]
	v_mfma_f32_16x16x32_bf16 v[88:91], v[144:147], v[160:163], v[88:91]
	v_mfma_f32_16x16x32_bf16 v[24:27], v[152:155], v[160:163], v[24:27]
	v_mfma_f32_16x16x32_bf16 v[80:83], v[144:147], v[178:181], v[80:83]
	v_mfma_f32_16x16x32_bf16 v[16:19], v[152:155], v[178:181], v[16:19]
	v_mfma_f32_16x16x32_bf16 v[72:75], v[144:147], v[186:189], v[72:75]
	v_mfma_f32_16x16x32_bf16 v[8:11], v[152:155], v[186:189], v[8:11]
	v_mfma_f32_16x16x32_bf16 v[64:67], v[144:147], v[202:205], v[64:67]
	v_mfma_f32_16x16x32_bf16 v[0:3], v[152:155], v[202:205], v[0:3]
	v_mfma_f32_16x16x32_bf16 v[88:91], v[148:151], v[164:167], v[88:91]
	v_mfma_f32_16x16x32_bf16 v[24:27], v[156:159], v[164:167], v[24:27]
	v_mfma_f32_16x16x32_bf16 v[80:83], v[148:151], v[182:185], v[80:83]
	v_mfma_f32_16x16x32_bf16 v[16:19], v[156:159], v[182:185], v[16:19]
	v_mfma_f32_16x16x32_bf16 v[72:75], v[148:151], v[198:201], v[72:75]
	v_mfma_f32_16x16x32_bf16 v[8:11], v[156:159], v[198:201], v[8:11]
	v_mfma_f32_16x16x32_bf16 v[64:67], v[148:151], v[220:223], v[64:67]
	v_mfma_f32_16x16x32_bf16 v[0:3], v[156:159], v[220:223], v[0:3]
	s_barrier
	s_add_i32 s19, s19, 2
	s_add_u32 s81, s81, 0x100
	s_addc_u32 s18, s18, 0
	s_add_u32 vcc_lo, vcc_lo, 0x100
	s_addc_u32 vcc_hi, vcc_hi, 0
	s_cmp_gt_u32 s19, 13
	s_cbranch_scc1 .Lkexit_6
